# grid barrier: waiters (non-leaders and non-last XCD leaders) poll the cross-XCD arrival counter TOP >= (gen+1)*nXCD instead of the release word bumped after the last leader's atomic returns; on top of
# speedup vs baseline: 1.0096x; 1.0000x over previous
; __device__ __forceinline__ unsigned xb_ld(unsigned* p)              { return __hip_atomic_load(p, __ATOMIC_RELAXED, __HIP_MEMORY_SCOPE_AGENT); }
; __device__ __forceinline__ unsigned xb_add(unsigned* p, unsigned v) { return __hip_atomic_fetch_add(p, v, __ATOMIC_RELAXED, __HIP_MEMORY_SCOPE_AGENT); }
; #define XB_SPIN(cond, bar) do { unsigned _sp = 0; while (cond) { __builtin_amdgcn_s_sleep(1); \
;     if ((++_sp & 255u) == 0u) { if (xb_ld(&(bar)[XB_TMO])) break; if (_sp > XB_SPIN_CAP) { atomicAdd(&(bar)[XB_TMO], 1u); break; } } } } while (0)
; __device__ __forceinline__ void xcd_barrier(const XcdBarrier& b, const int wid) {
;     ...
;         const unsigned old = xb_add(&bar[XB_XSUB(b.x)], 1u);
;         const unsigned gen = old / nloc;
;         if (old + 1u == (gen + 1u) * nloc) {
;             __builtin_amdgcn_fence(__ATOMIC_RELEASE, "agent");
;             asm volatile("s_waitcnt vmcnt(0)" ::: "memory");
;             const unsigned og = xb_add(&bar[XB_TOP], 1u);
;             const unsigned tg = og / nx;
;             if (og + 1u == (tg + 1u) * nx) xb_add(&bar[XB_TOPGEN], 1u);
;             else XB_SPIN(xb_ld(&bar[XB_TOPGEN]) == tg, bar);
;             __builtin_amdgcn_fence(__ATOMIC_ACQUIRE, "agent");
;             xb_add(&bar[XB_XGEN(b.x)], 1u);
;             asm volatile("s_waitcnt vmcnt(0)" ::: "memory");
;         } else {
;             XB_SPIN(xb_ld(&bar[XB_XGEN(b.x)]) == gen, bar);
;             __builtin_amdgcn_fence(__ATOMIC_ACQUIRE, "agent");
;             asm volatile("s_waitcnt vmcnt(0)" ::: "memory");
;         }
.LBB0_225:
	v_readlane_b32 s2, v254, 8
	s_lshl_b32 s2, s2, 8
	v_readlane_b32 s4, v254, 6
	v_readlane_b32 s5, v254, 7
	s_add_u32 s2, s4, s2
	s_addc_u32 s3, s5, 0
	v_mov_b32_e32 v1, 0x1000
	v_mov_b32_e32 v3, 1
	global_atomic_add v3, v1, v3, s[2:3] offset:1024 sc0
	v_cvt_f32_u32_e32 v1, v2
	v_sub_u32_e32 v4, 0, v2
	v_rcp_iflag_f32_e32 v1, v1
	s_nop 0
	v_mul_f32_e32 v1, 0x4f7ffffe, v1
	v_cvt_u32_f32_e32 v1, v1
	v_mul_lo_u32 v4, v4, v1
	v_mul_hi_u32 v4, v1, v4
	v_add_u32_e32 v1, v1, v4
	s_waitcnt vmcnt(0)
	v_mul_hi_u32 v1, v3, v1
	v_mul_lo_u32 v4, v1, v2
	v_sub_u32_e32 v4, v3, v4
	v_add_u32_e32 v5, 1, v1
	v_cmp_ge_u32_e32 vcc, v4, v2
	v_add_u32_e32 v3, 1, v3
	s_nop 0
	v_cndmask_b32_e32 v1, v1, v5, vcc
	v_sub_u32_e32 v5, v4, v2
	v_cndmask_b32_e32 v4, v4, v5, vcc
	v_add_u32_e32 v5, 1, v1
	v_cmp_ge_u32_e32 vcc, v4, v2
	s_nop 1
	v_cndmask_b32_e32 v1, v1, v5, vcc
	v_mul_lo_u32 v4, v2, v1
	v_add_u32_e32 v2, v4, v2
	v_cmp_ne_u32_e32 vcc, v3, v2
	s_and_saveexec_b64 s[4:5], vcc
	s_xor_b64 s[4:5], exec, s[4:5]
	s_cbranch_execz .LBB0_239
	s_waitcnt lgkmcnt(0)
	v_add_u32_e32 v1, 1, v1
	v_mul_lo_u32 v1, v1, v0
	v_mov_b32_e32 v0, 0
	s_add_u32 s10, s86, 0x7400
	s_addc_u32 s11, s87, 0
	global_load_dword v0, v0, s[10:11] sc1
	s_waitcnt vmcnt(0)
	v_cmp_lt_u32_e32 vcc, v0, v1
	s_and_saveexec_b64 s[6:7], vcc
	s_cbranch_execz .LBB0_238
	s_add_u32 s8, s86, 0x4200
	s_addc_u32 s9, s87, 0
	s_mov_b32 s22, 1
	s_mov_b64 s[12:13], 0
	v_mov_b32_e32 v0, 0
	s_branch .LBB0_229

; __device__ __forceinline__ unsigned xb_ld(unsigned* p)              { return __hip_atomic_load(p, __ATOMIC_RELAXED, __HIP_MEMORY_SCOPE_AGENT); }
; __device__ __forceinline__ unsigned xb_add(unsigned* p, unsigned v) { return __hip_atomic_fetch_add(p, v, __ATOMIC_RELAXED, __HIP_MEMORY_SCOPE_AGENT); }
; #define XB_SPIN(cond, bar) do { unsigned _sp = 0; while (cond) { __builtin_amdgcn_s_sleep(1); \
;     if ((++_sp & 255u) == 0u) { if (xb_ld(&(bar)[XB_TMO])) break; if (_sp > XB_SPIN_CAP) { atomicAdd(&(bar)[XB_TMO], 1u); break; } } } } while (0)
; __device__ __forceinline__ void xcd_barrier(const XcdBarrier& b, const int wid) {
;     ...
;             else XB_SPIN(xb_ld(&bar[XB_TOPGEN]) == tg, bar);
;             __builtin_amdgcn_fence(__ATOMIC_ACQUIRE, "agent");
;             xb_add(&bar[XB_XGEN(b.x)], 1u);
;             asm volatile("s_waitcnt vmcnt(0)" ::: "memory");
;         } else {
;             XB_SPIN(xb_ld(&bar[XB_XGEN(b.x)]) == gen, bar);
.LBB0_231:
	global_load_dword v2, v0, s[10:11] sc1
	s_add_i32 s22, s22, 1
	s_mov_b64 s[18:19], -1
	s_waitcnt vmcnt(0)
	v_cmp_ge_u32_e32 vcc, v2, v1
	s_orn2_b64 s[16:17], vcc, exec
	s_branch .LBB0_228

; __device__ __forceinline__ unsigned xb_ld(unsigned* p)              { return __hip_atomic_load(p, __ATOMIC_RELAXED, __HIP_MEMORY_SCOPE_AGENT); }
; __device__ __forceinline__ unsigned xb_add(unsigned* p, unsigned v) { return __hip_atomic_fetch_add(p, v, __ATOMIC_RELAXED, __HIP_MEMORY_SCOPE_AGENT); }
; #define XB_SPIN(cond, bar) do { unsigned _sp = 0; while (cond) { __builtin_amdgcn_s_sleep(1); \
;     if ((++_sp & 255u) == 0u) { if (xb_ld(&(bar)[XB_TMO])) break; if (_sp > XB_SPIN_CAP) { atomicAdd(&(bar)[XB_TMO], 1u); break; } } } } while (0)
; __device__ __forceinline__ void xcd_barrier(const XcdBarrier& b, const int wid) {
;     ...
;             const unsigned og = xb_add(&bar[XB_TOP], 1u);
;             const unsigned tg = og / nx;
;             if (og + 1u == (tg + 1u) * nx) xb_add(&bar[XB_TOPGEN], 1u);
;             else XB_SPIN(xb_ld(&bar[XB_TOPGEN]) == tg, bar);
;             __builtin_amdgcn_fence(__ATOMIC_ACQUIRE, "agent");
;             xb_add(&bar[XB_XGEN(b.x)], 1u);
;             asm volatile("s_waitcnt vmcnt(0)" ::: "memory");
.LBB0_242:
	s_or_b64 exec, exec, s[6:7]
	v_cvt_f32_u32_e32 v3, v0
	s_waitcnt vmcnt(0)
	v_readfirstlane_b32 s4, v2
	s_add_u32 s6, s86, 0x7500
	s_addc_u32 s7, s87, 0
	v_rcp_iflag_f32_e32 v3, v3
	v_add_u32_e32 v1, s4, v1
	v_add_u32_e32 v4, 1, v1
	s_mov_b64 s[8:9], -1
	v_mul_f32_e32 v2, 0x4f7ffffe, v3
	v_cvt_u32_f32_e32 v2, v2
	v_sub_u32_e32 v3, 0, v0
	v_mul_lo_u32 v3, v3, v2
	v_mul_hi_u32 v3, v2, v3
	v_add_u32_e32 v2, v2, v3
	v_mul_hi_u32 v2, v1, v2
	v_mul_lo_u32 v3, v2, v0
	v_sub_u32_e32 v1, v1, v3
	v_add_u32_e32 v5, 1, v2
	v_cmp_ge_u32_e32 vcc, v1, v0
	v_sub_u32_e32 v3, v1, v0
	s_nop 0
	v_cndmask_b32_e32 v2, v2, v5, vcc
	v_cndmask_b32_e32 v1, v1, v3, vcc
	v_add_u32_e32 v3, 1, v2
	v_cmp_ge_u32_e32 vcc, v1, v0
	s_nop 1
	v_cndmask_b32_e32 v2, v2, v3, vcc
	v_mul_lo_u32 v1, v0, v2
	v_add_u32_e32 v0, v1, v0
	v_cmp_ne_u32_e32 vcc, v4, v0
	v_mov_b32_e32 v5, v0
	v_mov_b64_e32 v[0:1], s[6:7]
	s_and_saveexec_b64 s[4:5], vcc
	s_cbranch_execz .LBB0_254
	v_mov_b32_e32 v0, 0
	global_load_dword v1, v0, s[6:7] offset:-256 sc1
	s_mov_b64 s[12:13], 0
	s_waitcnt vmcnt(0)
	v_cmp_lt_u32_e32 vcc, v1, v5
	s_and_saveexec_b64 s[10:11], vcc
	s_cbranch_execz .LBB0_253
	s_add_u32 s8, s86, 0x4200
	s_addc_u32 s9, s87, 0
	s_mov_b32 s22, 1
	s_branch .LBB0_246

; __device__ __forceinline__ unsigned xb_ld(unsigned* p)              { return __hip_atomic_load(p, __ATOMIC_RELAXED, __HIP_MEMORY_SCOPE_AGENT); }
; #define XB_SPIN(cond, bar) do { unsigned _sp = 0; while (cond) { __builtin_amdgcn_s_sleep(1); \
;     if ((++_sp & 255u) == 0u) { if (xb_ld(&(bar)[XB_TMO])) break; if (_sp > XB_SPIN_CAP) { atomicAdd(&(bar)[XB_TMO], 1u); break; } } } } while (0)
; __device__ __forceinline__ void xcd_barrier(const XcdBarrier& b, const int wid) {
;     ...
;             else XB_SPIN(xb_ld(&bar[XB_TOPGEN]) == tg, bar);
.LBB0_248:
	global_load_dword v1, v0, s[6:7] offset:-256 sc1
	s_add_i32 s22, s22, 1
	s_mov_b64 s[16:17], -1
	s_waitcnt vmcnt(0)
	v_cmp_ge_u32_e32 vcc, v1, v5
	s_orn2_b64 s[20:21], vcc, exec
	s_branch .LBB0_245
